# lane-swap S5 transpose + attention row-sum adds in MFMA shadows + early second-half QK reads + static priority for waves 4-7 in attention, on the cache-policy version (re-measure)
# speedup vs baseline: 1.0037x; 1.0037x over previous
; #define LAS __attribute__((address_space(3)))
; #define AT_STEP(sc0, sc1, sn0, sn1, tt, par, LS, SS) do { \
;             AT_LOAD(LS, (tt) + 3, (tt) + 2); \
;             bf16x8 pa_[4]; \
;             qk(sn0, sn1, (par) ^ 1); \
;             softmax_pack(sc0, sc1, pa_); \
;             pv(pa_, (par)); \
;             AT_STOREK(SS, (par)); AT_STOREV(SS, (par) ^ 1); \
;             __syncthreads(); } while (0)
; DI void attn_phase(const bf16_t* Qb, const bf16_t* Kb, const bf16_t* VT, bf16_t* MIX, LAS unsigned char* lds, int G, int bid, int tid, int wave, int lane) {
;     const int r32 = lane & 31, hi = lane >> 5;
;     LAS float* scrw = (LAS float*)(lds + 2 * AT_KB + 2 * AT_VB) + wave * 64;
;     constexpr int NU_LAT = NB * 8 * 16, NU = NU_LAT + NB * 8;
;     const int vcu = ((G & 7) == 0) ? (bid & 7) * (G >> 3) + (bid >> 3) : bid;
;     const int kc0 = tid, kc1 = 512 + tid, kc1c = 512 + (tid & 255);
;     const int kl0 = (kc0 / 12) * 208 + (kc0 % 12) * 16, kl1 = (kc1 / 12) * 208 + (kc1 % 12) * 16;
;     const int vd = tid >> 3, vch = tid & 7; const int vl = vd * 144 + vch * 16;
;     for (int u = vcu; u < NU; u += G) {
;     ...
;         AT_STEP(sA0, sA1, sB0, sB1, t, 0, A, B);
;         { bf16x8 pa_[4]; softmax_pack(sB0, sB1, pa_); pv(pa_, 1); }
;     ...
;         lsum += __shfl_xor(lsum, 32);
;         scrw[r32] = __builtin_amdgcn_rcpf(lsum);
.LBB0_441:
	s_and_b32 s1, s96, 7
	s_ashr_i32 s4, s33, 3
	s_mul_i32 s1, s1, s4
	s_ashr_i32 s4, s96, 3
	s_and_b32 s0, s33, 7
	s_add_i32 s1, s1, s4
	s_cmp_eq_u32 s0, 0
	v_readlane_b32 s36, v255, 6
	s_cselect_b32 s23, s1, s96
	v_readlane_b32 s37, v255, 7
	s_cmpk_gt_i32 s23, 0x87f
	v_readlane_b32 s37, v255, 5
	s_cbranch_scc1 .LBB0_462
	s_add_u32 s24, s84, 0x345dc000
	s_addc_u32 s25, s85, 0
	s_add_u32 s40, s84, 0x246dc000
	s_waitcnt vmcnt(5)
	v_lshlrev_b32_e32 v2, 4, v153
	s_addc_u32 s41, s85, 0
	s_lshl_b32 s0, s37, 8
	v_ashrrev_i32_e32 v12, 3, v153
	v_and_b32_e32 v148, 0x70, v2
	s_movk_i32 s9, 0x90
	s_add_i32 s8, s0, 0
	v_mad_u64_u32 v[2:3], s[0:1], v12, s9, v[148:149]
	v_add_u32_e32 v3, 0x200, v153
	s_mov_b32 s0, 0x2aaaaaab
	s_waitcnt vmcnt(4)
	v_mul_hi_i32 v4, v3, s0
	v_lshrrev_b32_e32 v5, 31, v4
	v_lshrrev_b32_e32 v4, 1, v4
	v_add_u32_e32 v4, v4, v5
	v_add_lshl_u32 v3, v4, v3, 4
	v_mul_hi_i32 v4, v153, s0
	v_lshrrev_b32_e32 v5, 31, v4
	v_lshrrev_b32_e32 v4, 1, v4
	v_lshrrev_b32_e32 v1, 5, v152
	v_add_u32_e32 v4, v4, v5
	v_add_lshl_u32 v13, v4, v153, 4
	v_lshlrev_b32_e32 v4, 4, v1
	v_mov_b32_e32 v5, v149
	v_lshl_add_u64 v[6:7], s[84:85], 0, v[4:5]
	s_mov_b64 s[0:1], 0x2dfdc000
	v_mov_b64_e32 v[10:11], s[84:85]
	v_lshl_add_u64 v[158:159], v[6:7], 0, s[0:1]
	v_mad_i64_i32 v[8:9], s[0:1], v12, s65, 0
	v_mad_i64_i32 v[10:11], s[0:1], v12, s65, v[10:11]
	s_movk_i32 s0, 0x100
	v_lshlrev_b32_e32 v160, 3, v153
	v_cmp_gt_i32_e64 s[4:5], s0, v153
	s_movk_i32 s0, 0xff
	v_and_b32_e32 v0, 31, v153
	v_and_b32_e32 v5, 0x7f8, v160
	v_cmp_lt_i32_e64 s[6:7], s0, v153
	s_movk_i32 s0, 0xd0
	s_lshl_b32 s42, s37, 5
	v_or_b32_e32 v6, 0x1000, v5
	v_mad_u32_u24 v5, v0, s0, 0
	v_lshl_add_u64 v[10:11], v[10:11], 0, v[148:149]
	s_mov_b64 s[0:1], 0x3abdc000
	s_ashr_i32 s43, s42, 31
	v_lshlrev_b32_e32 v12, 12, v1
	v_xor_b32_e32 v1, 32, v210
	v_lshl_add_u64 v[162:163], v[10:11], 0, s[0:1]
	v_readlane_b32 s0, v254, 22
	v_cmp_lt_i32_e32 vcc, v1, v250
	s_add_u32 s0, s0, s78
	v_readlane_b32 s1, v254, 23
	v_mad_u32_u24 v7, v0, s9, 0
	v_or_b32_e32 v14, 0x400, v12
	v_or_b32_e32 v16, 0x800, v12
	v_or_b32_e32 v18, 0xc00, v12
	v_or_b32_e32 v20, 0x2000, v12
	v_or_b32_e32 v22, 0x2400, v12
	v_or_b32_e32 v24, 0x2800, v12
	v_or_b32_e32 v26, 0x2c00, v12
	v_or_b32_e32 v28, 0x4000, v12
	v_or_b32_e32 v30, 0x4400, v12
	v_or_b32_e32 v32, 0x4800, v12
	v_or_b32_e32 v34, 0x4c00, v12
	v_or_b32_e32 v36, 0x6000, v12
	v_or_b32_e32 v38, 0x6400, v12
	v_or_b32_e32 v40, 0x6800, v12
	v_or_b32_e32 v42, 0x6c00, v12
	v_cndmask_b32_e32 v1, v210, v1, vcc
	v_or_b32_e32 v8, v8, v148
	s_addc_u32 s1, s1, s79
	v_or_b32_e32 v156, s42, v0
	v_mov_b32_e32 v157, s43
	v_ashrrev_i32_e32 v161, 31, v160
	v_lshl_add_u32 v155, v0, 2, s8
	v_add_u32_e32 v213, s8, v4
	v_lshlrev_b32_e32 v214, 2, v1
	v_lshl_add_u64 v[164:165], s[0:1], 0, v[8:9]
	v_lshlrev_b32_e32 v215, 1, v6
	v_lshlrev_b32_e32 v148, 1, v0
	v_lshlrev_b32_e32 v166, 1, v12
	v_lshlrev_b32_e32 v168, 1, v14
	v_lshlrev_b32_e32 v170, 1, v16
	v_lshlrev_b32_e32 v172, 1, v18
	v_lshlrev_b32_e32 v174, 1, v20
	v_lshlrev_b32_e32 v176, 1, v22
	v_lshlrev_b32_e32 v178, 1, v24
	v_lshlrev_b32_e32 v180, 1, v26
	v_lshlrev_b32_e32 v182, 1, v28
	v_lshlrev_b32_e32 v184, 1, v30
	v_lshlrev_b32_e32 v186, 1, v32
	v_lshlrev_b32_e32 v188, 1, v34
	v_lshlrev_b32_e32 v190, 1, v36
	v_lshlrev_b32_e32 v192, 1, v38
	v_lshlrev_b32_e32 v194, 1, v40
	v_lshlrev_b32_e32 v196, 1, v42
	v_add_u32_e32 v216, 0, v13
	v_add_u32_e32 v217, 0, v2
	v_add_u32_e32 v218, 0, v3
	v_add_u32_e32 v219, v5, v4
	v_add_u32_e32 v220, v7, v4
	v_readfirstlane_b32 s98, v153
	s_nop 3
	s_lshr_b32 s98, s98, 6
	s_cmp_ge_u32 s98, 4
	s_cbranch_scc0 .Lattn_prio_done
	s_setprio 1
.Lattn_prio_done:
	s_branch .LBB0_444
.LBB0_443:
	s_or_b64 exec, exec, s[8:9]
	v_add_f32_e32 v43, 0, v48
	v_add_f32_e32 v44, 0, v63
	v_add_f32_e32 v43, v49, v43
	v_add_f32_e32 v44, v62, v44
	v_add_f32_e32 v43, v50, v43
	v_add_f32_e32 v44, v61, v44
	v_add_f32_e32 v43, v51, v43
	v_add_f32_e32 v33, v33, v44
	v_add_f32_e32 v43, v52, v43
	v_add_f32_e32 v33, v34, v33
	v_add_f32_e32 v34, v53, v43
	v_add_f32_e32 v32, v32, v33
	v_add_f32_e32 v33, v54, v34
	v_add_f32_e32 v32, v36, v32
	v_add_f32_e32 v33, v55, v33
	v_add_f32_e32 v32, v35, v32
	v_add_f32_e32 v33, v102, v33
	v_add_f32_e32 v32, v108, v32
	v_add_f32_e32 v33, v101, v33
	v_add_f32_e32 v32, v103, v32
	v_add_f32_e32 v33, v100, v33
	v_add_f32_e32 v32, v42, v32
	v_add_f32_e32 v33, v59, v33
	v_add_f32_e32 v32, v40, v32
	v_add_f32_e32 v33, v60, v33
	v_add_f32_e32 v32, v41, v32
	v_add_f32_e32 v33, v57, v33
	v_add_f32_e32 v32, v38, v32
	v_add_f32_e32 v33, v58, v33
	v_add_f32_e32 v32, v39, v32
	v_add_f32_e32 v33, v56, v33
	v_add_f32_e32 v32, v37, v32
	v_add_f32_e32 v32, v33, v32
	v_add_f32_e32 v38, v167, v32
	v_exp_f32_e32 v32, v64
	v_exp_f32_e32 v33, v80
	v_exp_f32_e32 v34, v65
	v_exp_f32_e32 v35, v81
	v_exp_f32_e32 v44, v66
	v_exp_f32_e32 v45, v82
	v_exp_f32_e32 v46, v67
	v_exp_f32_e32 v47, v83
	v_pk_add_f32 v[36:37], v[32:33], 0 op_sel_hi:[1,0]
	v_exp_f32_e32 v48, v68
	v_exp_f32_e32 v49, v84
	v_pk_add_f32 v[36:37], v[34:35], v[36:37]
	v_exp_f32_e32 v50, v69
	v_exp_f32_e32 v51, v85
	v_pk_add_f32 v[36:37], v[44:45], v[36:37]
	v_exp_f32_e32 v52, v70
	v_exp_f32_e32 v53, v86
	v_pk_add_f32 v[36:37], v[46:47], v[36:37]
	v_exp_f32_e32 v54, v71
	v_exp_f32_e32 v55, v87
	v_exp_f32_e32 v56, v72
	v_exp_f32_e32 v57, v88
	v_pk_add_f32 v[36:37], v[48:49], v[36:37]
	v_exp_f32_e32 v58, v73
	v_exp_f32_e32 v59, v89
	v_pk_add_f32 v[36:37], v[50:51], v[36:37]
	v_exp_f32_e32 v60, v74
	v_exp_f32_e32 v61, v90
	v_pk_add_f32 v[36:37], v[52:53], v[36:37]
	v_exp_f32_e32 v62, v75
	v_exp_f32_e32 v63, v91
	v_pk_add_f32 v[36:37], v[54:55], v[36:37]
	v_exp_f32_e32 v64, v76
	v_exp_f32_e32 v65, v92
	v_pk_add_f32 v[36:37], v[56:57], v[36:37]
	v_exp_f32_e32 v66, v77
	v_exp_f32_e32 v67, v93
	v_pk_add_f32 v[36:37], v[58:59], v[36:37]
	v_exp_f32_e32 v68, v78
	v_exp_f32_e32 v69, v94
	v_pk_add_f32 v[36:37], v[60:61], v[36:37]
	v_exp_f32_e32 v70, v79
	v_exp_f32_e32 v71, v95
	v_pk_add_f32 v[36:37], v[62:63], v[36:37]
	v_cvt_pk_bf16_f32 v39, v52, v54
	v_pk_add_f32 v[36:37], v[64:65], v[36:37]
	s_waitcnt vmcnt(0)
	ds_write_b128 v217, v[96:99] offset:35840
	v_pk_add_f32 v[36:37], v[66:67], v[36:37]
	s_waitcnt lgkmcnt(0)
	v_pk_add_f32 v[36:37], v[68:69], v[36:37]
	s_barrier
; DI bf16_t f2bf(float f) { return (bf16_t)(pk2(f, 0.f) & 0xffffu); }
; #define LDS_WAIT() asm volatile("s_waitcnt lgkmcnt(0)" ::: "memory")
; DI int crow(int r, int hi) { return (r & 3) + 8 * (r >> 2) + 4 * hi; }
; #define AT_STEP(sc0, sc1, sn0, sn1, tt, par, LS, SS) do { \
;             AT_LOAD(LS, (tt) + 3, (tt) + 2); \
;             bf16x8 pa_[4]; \
;             qk(sn0, sn1, (par) ^ 1); \
;             softmax_pack(sc0, sc1, pa_); \
;             pv(pa_, (par)); \
;             AT_STOREK(SS, (par)); AT_STOREV(SS, (par) ^ 1); \
;             __syncthreads(); } while (0)
; DI void attn_phase(const bf16_t* Qb, const bf16_t* Kb, const bf16_t* VT, bf16_t* MIX, LAS unsigned char* lds, int G, int bid, int tid, int wave, int lane) {
;     ...
;         AT_STEP(sA0, sA1, sB0, sB1, t, 0, A, B);
;         { bf16x8 pa_[4]; softmax_pack(sB0, sB1, pa_); pv(pa_, 1); }
;     ...
;         lsum += __shfl_xor(lsum, 32);
;         scrw[r32] = __builtin_amdgcn_rcpf(lsum);
;         LDS_WAIT();
;         bf16_t* op = MIX + (orow0 + wave * 32) * D + h * 64 + r32;
; #pragma unroll
;         for (int r = 0; r < 16; ++r) { const int q = crow(r, hi); const float il = scrw[q];
;             op[(size_t)q * D] = f2bf(o0[r] * il); op[(size_t)q * D + 32] = f2bf(o1[r] * il); }
;         LDS_WAIT();
;         __syncthreads();
;     }
	v_pk_add_f32 v[36:37], v[70:71], v[36:37]
	s_nop 0
	v_add_f32_e32 v36, v36, v37
	v_add_f32_e32 v72, v38, v36
	v_cvt_pk_bf16_f32 v36, v32, v34
	v_cvt_pk_bf16_f32 v37, v44, v46
	v_cvt_pk_bf16_f32 v38, v48, v50
	v_cvt_pk_bf16_f32 v40, v56, v58
	v_cvt_pk_bf16_f32 v45, v45, v47
	v_cvt_pk_bf16_f32 v46, v49, v51
	v_cvt_pk_bf16_f32 v47, v53, v55
	v_cvt_pk_bf16_f32 v32, v57, v59
	ds_read_b128 v[48:51], v220 offset:40448
	ds_read_b128 v[52:55], v220 offset:35840
	ds_read_b128 v[56:59], v220 offset:35872
	s_waitcnt lgkmcnt(1)
	v_mfma_f32_32x32x16_bf16 v[16:31], v[36:39], v[52:55], v[16:31]
	v_cvt_pk_bf16_f32 v41, v60, v62
	v_cvt_pk_bf16_f32 v42, v64, v66
	v_cvt_pk_bf16_f32 v43, v68, v70
	v_cvt_pk_bf16_f32 v44, v33, v35
	v_cvt_pk_bf16_f32 v33, v61, v63
	v_cvt_pk_bf16_f32 v34, v65, v67
	v_cvt_pk_bf16_f32 v35, v69, v71
	v_mfma_f32_32x32x16_bf16 v[0:15], v[36:39], v[48:51], v[0:15]
	ds_read_b128 v[36:39], v220 offset:40480
	s_add_u32 s0, s0, s42
	s_addc_u32 s1, s1, s43
	s_lshl_b64 s[0:1], s[0:1], 11
	s_add_u32 s0, s40, s0
	s_addc_u32 s1, s41, s1
	s_lshl_b32 s8, s44, 7
	s_waitcnt lgkmcnt(1)
	v_mfma_f32_32x32x16_bf16 v[16:31], v[40:43], v[56:59], v[16:31]
	s_and_b32 s8, s8, 0x380
	s_add_u32 s0, s0, s8
	s_addc_u32 s1, s1, 0
	v_mov_b32_e32 v167, v149
	v_mov_b32_e32 v169, v149
	v_mov_b32_e32 v171, v149
	v_mov_b32_e32 v173, v149
	s_waitcnt lgkmcnt(0)
	v_mfma_f32_32x32x16_bf16 v[0:15], v[40:43], v[36:39], v[0:15]
	ds_read_b128 v[36:39], v220 offset:35904
	ds_read_b128 v[40:43], v220 offset:40512
	v_mov_b32_e32 v175, v149
	v_mov_b32_e32 v177, v149
	v_mov_b32_e32 v179, v149
	v_mov_b32_e32 v181, v149
	v_mov_b32_e32 v183, v149
	v_mov_b32_e32 v185, v149
	s_waitcnt lgkmcnt(1)
	v_mfma_f32_32x32x16_bf16 v[16:31], v[44:47], v[36:39], v[16:31]
	v_mov_b32_e32 v187, v149
	v_mov_b32_e32 v189, v149
	v_mov_b32_e32 v191, v149
	v_mov_b32_e32 v193, v149
	v_mov_b32_e32 v195, v149
	v_mov_b32_e32 v197, v149
	s_add_i32 s23, s23, s33
	s_waitcnt lgkmcnt(0)
	v_mfma_f32_32x32x16_bf16 v[0:15], v[44:47], v[40:43], v[0:15]
	ds_read_b128 v[36:39], v220 offset:35936
	ds_read_b128 v[40:43], v220 offset:40544
	s_cmpk_gt_i32 s23, 0x87f
	s_waitcnt lgkmcnt(1)
	v_mfma_f32_32x32x16_bf16 v[16:31], v[32:35], v[36:39], v[16:31]
	s_waitcnt lgkmcnt(0)
	v_mfma_f32_32x32x16_bf16 v[0:15], v[32:35], v[40:43], v[0:15]
	ds_bpermute_b32 v32, v214, v72
	v_lshl_add_u64 v[40:41], s[0:1], 0, v[148:149]
	v_lshl_add_u64 v[42:43], v[40:41], 0, v[166:167]
	s_waitcnt lgkmcnt(0)
	v_add_f32_e32 v32, v72, v32
	v_rcp_f32_e32 v32, v32
	ds_write_b32 v155, v32 offset:45056
	s_waitcnt lgkmcnt(0)
	ds_read_b128 v[32:35], v213 offset:45056
	ds_read_b128 v[36:39], v213 offset:45088
	s_waitcnt lgkmcnt(1)
	s_nop 1
	v_mul_f32_e32 v0, v0, v32
	v_mul_f32_e32 v16, v16, v32
	v_cvt_pk_bf16_f32 v0, v0, s0
	v_cvt_pk_bf16_f32 v16, v16, s0
	global_store_short v[42:43], v0, off offset:64
	v_mul_f32_e32 v0, v17, v33
	global_store_short v[42:43], v16, off
	v_cvt_pk_bf16_f32 v0, v0, s0
	v_lshl_add_u64 v[16:17], v[40:41], 0, v[168:169]
	global_store_short v[16:17], v0, off
	v_mul_f32_e32 v0, v1, v33
	v_cvt_pk_bf16_f32 v0, v0, s0
	global_store_short v[16:17], v0, off offset:64
	v_mul_f32_e32 v0, v18, v34
	v_mul_f32_e32 v2, v2, v34
	v_cvt_pk_bf16_f32 v16, v0, s0
	v_lshl_add_u64 v[0:1], v[40:41], 0, v[170:171]
	v_cvt_pk_bf16_f32 v2, v2, s0
	global_store_short v[0:1], v16, off
	global_store_short v[0:1], v2, off offset:64
	v_mul_f32_e32 v0, v19, v35
	v_cvt_pk_bf16_f32 v2, v0, s0
	v_lshl_add_u64 v[0:1], v[40:41], 0, v[172:173]
	global_store_short v[0:1], v2, off
	v_mul_f32_e32 v2, v3, v35
	v_cvt_pk_bf16_f32 v2, v2, s0
	global_store_short v[0:1], v2, off offset:64
	s_waitcnt lgkmcnt(0)
	v_mul_f32_e32 v0, v20, v36
	v_cvt_pk_bf16_f32 v2, v0, s0
	v_lshl_add_u64 v[0:1], v[40:41], 0, v[174:175]
	global_store_short v[0:1], v2, off
	v_mul_f32_e32 v2, v4, v36
	v_cvt_pk_bf16_f32 v2, v2, s0
	global_store_short v[0:1], v2, off offset:64
	v_mul_f32_e32 v0, v21, v37
	v_cvt_pk_bf16_f32 v2, v0, s0
	v_lshl_add_u64 v[0:1], v[40:41], 0, v[176:177]
	global_store_short v[0:1], v2, off
	v_mul_f32_e32 v2, v5, v37
	v_cvt_pk_bf16_f32 v2, v2, s0
	global_store_short v[0:1], v2, off offset:64
	v_mul_f32_e32 v0, v22, v38
	v_cvt_pk_bf16_f32 v2, v0, s0
	v_lshl_add_u64 v[0:1], v[40:41], 0, v[178:179]
	global_store_short v[0:1], v2, off
	v_mul_f32_e32 v2, v6, v38
	v_cvt_pk_bf16_f32 v2, v2, s0
	global_store_short v[0:1], v2, off offset:64
	v_mul_f32_e32 v0, v23, v39
	v_cvt_pk_bf16_f32 v2, v0, s0
	v_lshl_add_u64 v[0:1], v[40:41], 0, v[180:181]
	global_store_short v[0:1], v2, off
	v_mul_f32_e32 v2, v7, v39
	v_cvt_pk_bf16_f32 v2, v2, s0
	global_store_short v[0:1], v2, off offset:64
	ds_read_b128 v[0:3], v213 offset:45120
	ds_read_b128 v[4:7], v213 offset:45152
	s_waitcnt lgkmcnt(1)
	v_mul_f32_e32 v16, v24, v0
	v_mul_f32_e32 v0, v8, v0
	v_cvt_pk_bf16_f32 v18, v16, s0
	v_lshl_add_u64 v[16:17], v[40:41], 0, v[182:183]
	v_cvt_pk_bf16_f32 v0, v0, s0
	global_store_short v[16:17], v0, off offset:64
	v_mul_f32_e32 v0, v25, v1
	global_store_short v[16:17], v18, off
	v_cvt_pk_bf16_f32 v0, v0, s0
	v_lshl_add_u64 v[16:17], v[40:41], 0, v[184:185]
	global_store_short v[16:17], v0, off
	v_mul_f32_e32 v0, v9, v1
	v_cvt_pk_bf16_f32 v0, v0, s0
	global_store_short v[16:17], v0, off offset:64
	v_mul_f32_e32 v0, v26, v2
	v_mul_f32_e32 v2, v10, v2
	v_cvt_pk_bf16_f32 v8, v0, s0
	v_lshl_add_u64 v[0:1], v[40:41], 0, v[186:187]
	v_cvt_pk_bf16_f32 v2, v2, s0
	global_store_short v[0:1], v8, off
	global_store_short v[0:1], v2, off offset:64
	v_mul_f32_e32 v0, v27, v3
	v_cvt_pk_bf16_f32 v2, v0, s0
	v_lshl_add_u64 v[0:1], v[40:41], 0, v[188:189]
	global_store_short v[0:1], v2, off
	v_mul_f32_e32 v2, v11, v3
	v_cvt_pk_bf16_f32 v2, v2, s0
	global_store_short v[0:1], v2, off offset:64
	s_waitcnt lgkmcnt(0)
	v_mul_f32_e32 v0, v28, v4
	v_cvt_pk_bf16_f32 v2, v0, s0
	v_lshl_add_u64 v[0:1], v[40:41], 0, v[190:191]
	global_store_short v[0:1], v2, off
	v_mul_f32_e32 v2, v12, v4
	v_cvt_pk_bf16_f32 v2, v2, s0
	global_store_short v[0:1], v2, off offset:64
	v_mul_f32_e32 v0, v29, v5
	v_cvt_pk_bf16_f32 v2, v0, s0
	v_lshl_add_u64 v[0:1], v[40:41], 0, v[192:193]
	global_store_short v[0:1], v2, off
	v_mul_f32_e32 v2, v13, v5
	v_cvt_pk_bf16_f32 v2, v2, s0
	global_store_short v[0:1], v2, off offset:64
	v_mul_f32_e32 v0, v30, v6
	v_cvt_pk_bf16_f32 v2, v0, s0
	v_lshl_add_u64 v[0:1], v[40:41], 0, v[194:195]
	global_store_short v[0:1], v2, off
	v_mul_f32_e32 v2, v14, v6
	v_cvt_pk_bf16_f32 v2, v2, s0
	global_store_short v[0:1], v2, off offset:64
	v_mul_f32_e32 v0, v31, v7
	v_cvt_pk_bf16_f32 v2, v0, s0
	v_lshl_add_u64 v[0:1], v[40:41], 0, v[196:197]
	global_store_short v[0:1], v2, off
	v_mul_f32_e32 v2, v15, v7
	v_cvt_pk_bf16_f32 v2, v2, s0
	global_store_short v[0:1], v2, off offset:64
	s_waitcnt lgkmcnt(0)
	s_barrier
	s_cbranch_scc1 .LBB0_462

; DI void attn_phase(const bf16_t* Qb, const bf16_t* Kb, const bf16_t* VT, bf16_t* MIX, LAS unsigned char* lds, int G, int bid, int tid, int wave, int lane) {
;     ...
;     }
; }
.LBB0_462:
	s_setprio 0
	s_mov_b64 s[0:1], 0
